# v102 + 44 always-satisfied s_waitcnt lgkmcnt(0) deleted in the prep_run rope section (the lane^4 exchanges are DPP moves now)
# baseline (speedup 1.0000x reference)
.LBB0_473:
	s_or_b64 exec, exec, s[4:5]
	v_lshrrev_b32_e32 v9, 6, v9
	v_and_b32_e32 v17, 63, v26
	v_cndmask_b32_e64 v9, v17, v9, s[38:39]
	v_cvt_f32_ubyte0_e32 v9, v9
	v_mul_f32_e32 v17, v59, v9
	v_mul_f32_e32 v17, 0.15915494, v17
	v_cos_f32_e32 v51, v17
	v_sin_f32_e32 v56, v17
	v_mul_f32_e32 v17, v60, v9
	v_mul_f32_e32 v17, 0.15915494, v17
	v_cos_f32_e32 v49, v17
	v_sin_f32_e32 v50, v17
	v_mul_f32_e32 v17, v61, v9
	v_lshlrev_b32_e32 v53, 16, v47
	v_lshlrev_b32_e32 v52, 16, v46
	v_and_b32_e32 v47, 0xffff0000, v47
	v_and_b32_e32 v46, 0xffff0000, v46
	v_mul_f32_e32 v17, 0.15915494, v17
	v_mul_f32_e32 v9, v62, v9
	v_pk_mul_f32 v[54:55], v[46:47], v[46:47]
	v_cos_f32_e32 v25, v17
	v_sin_f32_e32 v48, v17
	v_mul_f32_e32 v17, 0.15915494, v9
	v_pk_fma_f32 v[54:55], v[52:53], v[52:53], v[54:55]
	v_cos_f32_e32 v9, v17
	v_sin_f32_e32 v21, v17
	v_add_f32_e32 v17, v54, v55
	v_mov_b32_e32 v55, v1
	s_nop 0
	v_add_f32_dpp v17, v17, v17 quad_perm:[1,0,3,2] row_mask:0xf bank_mask:0xf bound_ctrl:1
	s_nop 1
	v_add_f32_dpp v17, v17, v17 quad_perm:[2,3,0,1] row_mask:0xf bank_mask:0xf bound_ctrl:1
	s_nop 1
	v_add_f32_dpp v17, v17, v17 row_ror:4 row_mask:0xf bank_mask:0xf bound_ctrl:1
	s_nop 1
	v_add_f32_dpp v17, v17, v17 row_ror:8 row_mask:0xf bank_mask:0xf bound_ctrl:1
	v_fmamk_f32 v17, v17, 0x3c800000, v237
	v_rsq_f32_e32 v23, v17
	s_nop 0
	v_mul_f32_e32 v17, v23, v52
	v_mul_f32_e32 v17, v0, v17
	s_nop 1
	v_mov_b32_dpp v52, v17 row_shr:4 row_mask:0xf bank_mask:0xa
	v_mov_b32_dpp v52, v17 row_shl:4 row_mask:0xf bank_mask:0x5
	v_mul_f32_e32 v205, v23, v46
	s_waitcnt lgkmcnt(0)
	v_mul_f32_e32 v52, v56, v52
	v_cndmask_b32_e64 v52, v52, -v52, s[36:37]
	v_fmac_f32_e32 v52, v51, v17
	v_cndmask_b32_e64 v54, v52, v17, s[40:41]
	v_pk_mul_f32 v[54:55], v[54:55], v[204:205]
	s_nop 1
	v_mov_b32_dpp v17, v55 row_shr:4 row_mask:0xf bank_mask:0xa
	v_mov_b32_dpp v17, v55 row_shl:4 row_mask:0xf bank_mask:0x5
	v_mul_f32_e32 v205, v23, v53
	v_cndmask_b32_e64 v46, v54, v54, s[40:41]
	v_cndmask_b32_e64 v46, v46, v46, s[40:41]
	v_cndmask_b32_e64 v46, v46, v46, s[40:41]
	v_mul_f32_e32 v17, v50, v17
	v_cndmask_b32_e64 v17, v17, -v17, s[36:37]
	v_fmac_f32_e32 v17, v49, v55
	v_cndmask_b32_e64 v17, v17, v55, s[40:41]
	v_pk_mov_b32 v[52:53], v[16:17], v[2:3] op_sel:[1,0]
	s_nop 0
	v_pk_mul_f32 v[52:53], v[52:53], v[204:205]
	s_nop 1
	v_mov_b32_dpp v54, v53 row_shr:4 row_mask:0xf bank_mask:0xa
	v_mov_b32_dpp v54, v53 row_shl:4 row_mask:0xf bank_mask:0x5
	v_mov_b32_e32 v17, v52
	v_cndmask_b32_e64 v17, v17, v52, s[40:41]
	v_mul_f32_e32 v205, v23, v47
	v_mul_f32_e32 v54, v48, v54
	v_cndmask_b32_e64 v54, v54, -v54, s[36:37]
	v_fmac_f32_e32 v54, v25, v53
	v_cndmask_b32_e64 v52, v54, v53, s[40:41]
	v_mov_b32_e32 v53, v3
	v_pk_mul_f32 v[52:53], v[52:53], v[204:205]
	s_nop 1
	v_mov_b32_dpp v23, v53 row_shr:4 row_mask:0xf bank_mask:0xa
	v_mov_b32_dpp v23, v53 row_shl:4 row_mask:0xf bank_mask:0x5
	v_cndmask_b32_e64 v47, v52, v52, s[40:41]
	v_cndmask_b32_e64 v52, v17, v17, s[40:41]
	v_cvt_pk_bf16_f32 v46, v46, v52
	v_mul_f32_e32 v23, v21, v23
	v_cndmask_b32_e64 v23, v23, -v23, s[36:37]
	v_fmac_f32_e32 v23, v9, v53
	v_cndmask_b32_e64 v17, v23, v53, s[40:41]
	v_mul_f32_e32 v17, 0x3e38aa3b, v17
	v_mov_b32_e32 v23, v161
	v_cvt_pk_bf16_f32 v47, v47, v17
	v_lshl_add_u64 v[52:53], v[34:35], 0, v[22:23]
	global_store_dwordx2 v[52:53], v[46:47], off offset:512
	v_lshlrev_b32_e32 v47, 16, v45
	v_lshlrev_b32_e32 v46, 16, v44
	v_and_b32_e32 v45, 0xffff0000, v45
	v_and_b32_e32 v44, 0xffff0000, v44
	v_pk_mul_f32 v[52:53], v[44:45], v[44:45]
	s_nop 0
	v_pk_fma_f32 v[52:53], v[46:47], v[46:47], v[52:53]
	s_nop 0
	v_add_f32_e32 v17, v52, v53
	v_mov_b32_e32 v53, v1
	s_nop 0
	v_add_f32_dpp v17, v17, v17 quad_perm:[1,0,3,2] row_mask:0xf bank_mask:0xf bound_ctrl:1
	s_nop 1
	v_add_f32_dpp v17, v17, v17 quad_perm:[2,3,0,1] row_mask:0xf bank_mask:0xf bound_ctrl:1
	s_nop 1
	v_add_f32_dpp v17, v17, v17 row_ror:4 row_mask:0xf bank_mask:0xf bound_ctrl:1
	s_nop 1
	v_add_f32_dpp v17, v17, v17 row_ror:8 row_mask:0xf bank_mask:0xf bound_ctrl:1
	v_fmamk_f32 v17, v17, 0x3c800000, v237
	v_rsq_f32_e32 v23, v17
	s_nop 0
	v_mul_f32_e32 v17, v23, v46
	v_mul_f32_e32 v17, v0, v17
	s_nop 1
	v_mov_b32_dpp v46, v17 row_shr:4 row_mask:0xf bank_mask:0xa
	v_mov_b32_dpp v46, v17 row_shl:4 row_mask:0xf bank_mask:0x5
	v_mul_f32_e32 v205, v23, v44
	v_mul_f32_e32 v46, v56, v46
	v_cndmask_b32_e64 v46, v46, -v46, s[36:37]
	v_fmac_f32_e32 v46, v51, v17
	v_cndmask_b32_e64 v52, v46, v17, s[40:41]
	v_pk_mul_f32 v[52:53], v[52:53], v[204:205]
	s_nop 1
	v_mov_b32_dpp v17, v53 row_shr:4 row_mask:0xf bank_mask:0xa
	v_mov_b32_dpp v17, v53 row_shl:4 row_mask:0xf bank_mask:0x5
	v_mul_f32_e32 v205, v23, v47
	v_cndmask_b32_e64 v44, v52, v52, s[40:41]
	v_cndmask_b32_e64 v44, v44, v44, s[40:41]
	v_cndmask_b32_e64 v44, v44, v44, s[40:41]
	v_mul_f32_e32 v17, v50, v17
	v_cndmask_b32_e64 v17, v17, -v17, s[36:37]
	v_fmac_f32_e32 v17, v49, v53
	v_cndmask_b32_e64 v17, v17, v53, s[40:41]
	v_pk_mov_b32 v[46:47], v[16:17], v[2:3] op_sel:[1,0]
	s_nop 0
	v_pk_mul_f32 v[46:47], v[46:47], v[204:205]
	s_nop 1
	v_mov_b32_dpp v52, v47 row_shr:4 row_mask:0xf bank_mask:0xa
	v_mov_b32_dpp v52, v47 row_shl:4 row_mask:0xf bank_mask:0x5
	v_mov_b32_e32 v17, v46
	v_cndmask_b32_e64 v17, v17, v46, s[40:41]
	v_mul_f32_e32 v205, v23, v45
	v_cndmask_b32_e64 v17, v17, v17, s[40:41]
	v_mul_f32_e32 v52, v48, v52
	v_cndmask_b32_e64 v52, v52, -v52, s[36:37]
	v_fmac_f32_e32 v52, v25, v47
	v_cndmask_b32_e64 v46, v52, v47, s[40:41]
	v_mov_b32_e32 v47, v3
	v_pk_mul_f32 v[46:47], v[46:47], v[204:205]
	s_nop 1
	v_mov_b32_dpp v23, v47 row_shr:4 row_mask:0xf bank_mask:0xa
	v_mov_b32_dpp v23, v47 row_shl:4 row_mask:0xf bank_mask:0x5
	v_cndmask_b32_e64 v45, v46, v46, s[40:41]
	v_cvt_pk_bf16_f32 v44, v44, v17
	v_mov_b32_e32 v17, v161
	v_mul_f32_e32 v23, v21, v23
	v_cndmask_b32_e64 v23, v23, -v23, s[36:37]
	v_fmac_f32_e32 v23, v9, v47
	v_cndmask_b32_e64 v23, v23, v47, s[40:41]
	v_mul_f32_e32 v23, 0x3e38aa3b, v23
	v_cvt_pk_bf16_f32 v45, v45, v23
	v_lshl_add_u64 v[46:47], v[34:35], 0, v[16:17]
	global_store_dwordx2 v[46:47], v[44:45], off offset:512
	v_lshlrev_b32_e32 v45, 16, v39
	v_lshlrev_b32_e32 v44, 16, v38
	v_and_b32_e32 v39, 0xffff0000, v39
	v_and_b32_e32 v38, 0xffff0000, v38
	v_pk_mul_f32 v[46:47], v[38:39], v[38:39]
	s_nop 0
	v_pk_fma_f32 v[46:47], v[44:45], v[44:45], v[46:47]
	s_nop 0
	v_add_f32_e32 v17, v46, v47
	s_nop 1
	v_add_f32_dpp v17, v17, v17 quad_perm:[1,0,3,2] row_mask:0xf bank_mask:0xf bound_ctrl:1
	s_nop 1
	v_add_f32_dpp v17, v17, v17 quad_perm:[2,3,0,1] row_mask:0xf bank_mask:0xf bound_ctrl:1
	s_nop 1
	v_add_f32_dpp v17, v17, v17 row_ror:4 row_mask:0xf bank_mask:0xf bound_ctrl:1
	s_nop 1
	v_add_f32_dpp v17, v17, v17 row_ror:8 row_mask:0xf bank_mask:0xf bound_ctrl:1
	v_fmamk_f32 v17, v17, 0x3c800000, v237
	v_rsq_f32_e32 v46, v17
	s_nop 0
	v_mul_f32_e32 v17, v46, v44
	v_mul_f32_e32 v17, v4, v17
	s_nop 1
	v_mov_b32_dpp v23, v17 row_shr:4 row_mask:0xf bank_mask:0xa
	v_mov_b32_dpp v23, v17 row_shl:4 row_mask:0xf bank_mask:0x5
	v_mul_f32_e32 v23, v56, v23
	v_cndmask_b32_e64 v23, v23, -v23, s[36:37]
	v_fmac_f32_e32 v23, v51, v17
	v_cndmask_b32_e64 v17, v23, v17, s[40:41]
	v_mul_f32_e32 v23, v46, v38
	v_mul_f32_e32 v23, v5, v23
	s_nop 1
	v_mov_b32_dpp v38, v23 row_shr:4 row_mask:0xf bank_mask:0xa
	v_mov_b32_dpp v38, v23 row_shl:4 row_mask:0xf bank_mask:0x5
	v_mul_f32_e32 v38, v50, v38
	v_cndmask_b32_e64 v38, v38, -v38, s[36:37]
	v_fmac_f32_e32 v38, v49, v23
	v_cndmask_b32_e64 v23, v38, v23, s[40:41]
	v_mul_f32_e32 v38, v46, v45
	v_mul_f32_e32 v38, v6, v38
	s_nop 1
	v_mov_b32_dpp v44, v38 row_shr:4 row_mask:0xf bank_mask:0xa
	v_mov_b32_dpp v44, v38 row_shl:4 row_mask:0xf bank_mask:0x5
	v_mul_f32_e32 v44, v48, v44
	v_cndmask_b32_e64 v44, v44, -v44, s[36:37]
	v_fmac_f32_e32 v44, v25, v38
	v_cndmask_b32_e64 v25, v44, v38, s[40:41]
	v_mul_f32_e32 v38, v46, v39
	v_mul_f32_e32 v38, v7, v38
	s_nop 1
	v_mov_b32_dpp v39, v38 row_shr:4 row_mask:0xf bank_mask:0xa
	v_mov_b32_dpp v39, v38 row_shl:4 row_mask:0xf bank_mask:0x5
	v_mul_f32_e32 v21, v21, v39
	v_cndmask_b32_e64 v21, v21, -v21, s[36:37]
	v_fmac_f32_e32 v21, v9, v38
	v_cndmask_b32_e64 v9, v21, v38, s[40:41]
	s_and_saveexec_b64 s[0:1], vcc
	s_cbranch_execz .LBB0_452
	v_cvt_pk_bf16_f32 v39, v25, v9
	v_mov_b32_e32 v25, v161
	v_cvt_pk_bf16_f32 v38, v17, v23
	v_lshl_add_u64 v[34:35], v[34:35], 0, v[24:25]
	global_store_dwordx2 v[34:35], v[38:39], off offset:512
	s_branch .LBB0_452

.LBB0_498:
	s_or_b64 exec, exec, s[2:3]
	v_lshrrev_b32_e32 v9, 6, v9
	v_and_b32_e32 v17, 63, v26
	v_cndmask_b32_e64 v9, v17, v9, s[38:39]
	v_cvt_f32_ubyte0_e32 v9, v9
	v_mul_f32_e32 v17, v59, v9
	v_mul_f32_e32 v17, 0.15915494, v17
	v_cos_f32_e32 v51, v17
	v_sin_f32_e32 v56, v17
	v_mul_f32_e32 v17, v60, v9
	v_mul_f32_e32 v17, 0.15915494, v17
	v_cos_f32_e32 v49, v17
	v_sin_f32_e32 v50, v17
	v_mul_f32_e32 v17, v61, v9
	v_lshlrev_b32_e32 v53, 16, v47
	v_lshlrev_b32_e32 v52, 16, v46
	v_and_b32_e32 v47, 0xffff0000, v47
	v_and_b32_e32 v46, 0xffff0000, v46
	v_mul_f32_e32 v17, 0.15915494, v17
	v_mul_f32_e32 v9, v62, v9
	v_pk_mul_f32 v[54:55], v[46:47], v[46:47]
	v_cos_f32_e32 v25, v17
	v_sin_f32_e32 v48, v17
	v_mul_f32_e32 v17, 0.15915494, v9
	v_pk_fma_f32 v[54:55], v[52:53], v[52:53], v[54:55]
	v_cos_f32_e32 v9, v17
	v_sin_f32_e32 v21, v17
	v_add_f32_e32 v17, v54, v55
	v_mov_b32_e32 v55, v1
	s_nop 0
	v_add_f32_dpp v17, v17, v17 quad_perm:[1,0,3,2] row_mask:0xf bank_mask:0xf bound_ctrl:1
	s_nop 1
	v_add_f32_dpp v17, v17, v17 quad_perm:[2,3,0,1] row_mask:0xf bank_mask:0xf bound_ctrl:1
	s_nop 1
	v_add_f32_dpp v17, v17, v17 row_ror:4 row_mask:0xf bank_mask:0xf bound_ctrl:1
	s_nop 1
	v_add_f32_dpp v17, v17, v17 row_ror:8 row_mask:0xf bank_mask:0xf bound_ctrl:1
	v_fmamk_f32 v17, v17, 0x3c800000, v237
	v_rsq_f32_e32 v23, v17
	s_nop 0
	v_mul_f32_e32 v17, v23, v52
	v_mul_f32_e32 v17, v0, v17
	s_nop 1
	v_mov_b32_dpp v52, v17 row_shr:4 row_mask:0xf bank_mask:0xa
	v_mov_b32_dpp v52, v17 row_shl:4 row_mask:0xf bank_mask:0x5
	v_mul_f32_e32 v205, v23, v46
	s_waitcnt lgkmcnt(0)
	v_mul_f32_e32 v52, v56, v52
	v_cndmask_b32_e64 v52, v52, -v52, s[36:37]
	v_fmac_f32_e32 v52, v51, v17
	v_cndmask_b32_e64 v54, v52, v17, s[40:41]
	v_pk_mul_f32 v[54:55], v[54:55], v[204:205]
	s_nop 1
	v_mov_b32_dpp v17, v55 row_shr:4 row_mask:0xf bank_mask:0xa
	v_mov_b32_dpp v17, v55 row_shl:4 row_mask:0xf bank_mask:0x5
	v_mul_f32_e32 v205, v23, v53
	v_cndmask_b32_e64 v46, v54, v54, s[40:41]
	v_cndmask_b32_e64 v46, v46, v46, s[40:41]
	v_cndmask_b32_e64 v46, v46, v46, s[40:41]
	v_mul_f32_e32 v17, v50, v17
	v_cndmask_b32_e64 v17, v17, -v17, s[36:37]
	v_fmac_f32_e32 v17, v49, v55
	v_cndmask_b32_e64 v17, v17, v55, s[40:41]
	v_pk_mov_b32 v[52:53], v[16:17], v[2:3] op_sel:[1,0]
	s_nop 0
	v_pk_mul_f32 v[52:53], v[52:53], v[204:205]
	s_nop 1
	v_mov_b32_dpp v54, v53 row_shr:4 row_mask:0xf bank_mask:0xa
	v_mov_b32_dpp v54, v53 row_shl:4 row_mask:0xf bank_mask:0x5
	v_mov_b32_e32 v17, v52
	v_cndmask_b32_e64 v17, v17, v52, s[40:41]
	v_mul_f32_e32 v205, v23, v47
	v_mul_f32_e32 v54, v48, v54
	v_cndmask_b32_e64 v54, v54, -v54, s[36:37]
	v_fmac_f32_e32 v54, v25, v53
	v_cndmask_b32_e64 v52, v54, v53, s[40:41]
	v_mov_b32_e32 v53, v3
	v_pk_mul_f32 v[52:53], v[52:53], v[204:205]
	s_nop 1
	v_mov_b32_dpp v23, v53 row_shr:4 row_mask:0xf bank_mask:0xa
	v_mov_b32_dpp v23, v53 row_shl:4 row_mask:0xf bank_mask:0x5
	v_cndmask_b32_e64 v47, v52, v52, s[40:41]
	v_cndmask_b32_e64 v52, v17, v17, s[40:41]
	v_cvt_pk_bf16_f32 v46, v46, v52
	v_mul_f32_e32 v23, v21, v23
	v_cndmask_b32_e64 v23, v23, -v23, s[36:37]
	v_fmac_f32_e32 v23, v9, v53
	v_cndmask_b32_e64 v17, v23, v53, s[40:41]
	v_mul_f32_e32 v17, 0x3e38aa3b, v17
	v_mov_b32_e32 v23, v161
	v_cvt_pk_bf16_f32 v47, v47, v17
	v_lshl_add_u64 v[52:53], v[34:35], 0, v[22:23]
	global_store_dwordx2 v[52:53], v[46:47], off offset:512
	v_lshlrev_b32_e32 v47, 16, v45
	v_lshlrev_b32_e32 v46, 16, v44
	v_and_b32_e32 v45, 0xffff0000, v45
	v_and_b32_e32 v44, 0xffff0000, v44
	v_pk_mul_f32 v[52:53], v[44:45], v[44:45]
	s_nop 0
	v_pk_fma_f32 v[52:53], v[46:47], v[46:47], v[52:53]
	s_nop 0
	v_add_f32_e32 v17, v52, v53
	v_mov_b32_e32 v53, v1
	s_nop 0
	v_add_f32_dpp v17, v17, v17 quad_perm:[1,0,3,2] row_mask:0xf bank_mask:0xf bound_ctrl:1
	s_nop 1
	v_add_f32_dpp v17, v17, v17 quad_perm:[2,3,0,1] row_mask:0xf bank_mask:0xf bound_ctrl:1
	s_nop 1
	v_add_f32_dpp v17, v17, v17 row_ror:4 row_mask:0xf bank_mask:0xf bound_ctrl:1
	s_nop 1
	v_add_f32_dpp v17, v17, v17 row_ror:8 row_mask:0xf bank_mask:0xf bound_ctrl:1
	v_fmamk_f32 v17, v17, 0x3c800000, v237
	v_rsq_f32_e32 v23, v17
	s_nop 0
	v_mul_f32_e32 v17, v23, v46
	v_mul_f32_e32 v17, v0, v17
	s_nop 1
	v_mov_b32_dpp v46, v17 row_shr:4 row_mask:0xf bank_mask:0xa
	v_mov_b32_dpp v46, v17 row_shl:4 row_mask:0xf bank_mask:0x5
	v_mul_f32_e32 v205, v23, v44
	v_mul_f32_e32 v46, v56, v46
	v_cndmask_b32_e64 v46, v46, -v46, s[36:37]
	v_fmac_f32_e32 v46, v51, v17
	v_cndmask_b32_e64 v52, v46, v17, s[40:41]
	v_pk_mul_f32 v[52:53], v[52:53], v[204:205]
	s_nop 1
	v_mov_b32_dpp v17, v53 row_shr:4 row_mask:0xf bank_mask:0xa
	v_mov_b32_dpp v17, v53 row_shl:4 row_mask:0xf bank_mask:0x5
	v_mul_f32_e32 v205, v23, v47
	v_cndmask_b32_e64 v44, v52, v52, s[40:41]
	v_cndmask_b32_e64 v44, v44, v44, s[40:41]
	v_cndmask_b32_e64 v44, v44, v44, s[40:41]
	v_mul_f32_e32 v17, v50, v17
	v_cndmask_b32_e64 v17, v17, -v17, s[36:37]
	v_fmac_f32_e32 v17, v49, v53
	v_cndmask_b32_e64 v17, v17, v53, s[40:41]
	v_pk_mov_b32 v[46:47], v[16:17], v[2:3] op_sel:[1,0]
	s_nop 0
	v_pk_mul_f32 v[46:47], v[46:47], v[204:205]
	s_nop 1
	v_mov_b32_dpp v52, v47 row_shr:4 row_mask:0xf bank_mask:0xa
	v_mov_b32_dpp v52, v47 row_shl:4 row_mask:0xf bank_mask:0x5
	v_mov_b32_e32 v17, v46
	v_cndmask_b32_e64 v17, v17, v46, s[40:41]
	v_mul_f32_e32 v205, v23, v45
	v_cndmask_b32_e64 v17, v17, v17, s[40:41]
	v_mul_f32_e32 v52, v48, v52
	v_cndmask_b32_e64 v52, v52, -v52, s[36:37]
	v_fmac_f32_e32 v52, v25, v47
	v_cndmask_b32_e64 v46, v52, v47, s[40:41]
	v_mov_b32_e32 v47, v3
	v_pk_mul_f32 v[46:47], v[46:47], v[204:205]
	s_nop 1
	v_mov_b32_dpp v23, v47 row_shr:4 row_mask:0xf bank_mask:0xa
	v_mov_b32_dpp v23, v47 row_shl:4 row_mask:0xf bank_mask:0x5
	v_cndmask_b32_e64 v45, v46, v46, s[40:41]
	v_cvt_pk_bf16_f32 v44, v44, v17
	v_mov_b32_e32 v17, v161
	v_mul_f32_e32 v23, v21, v23
	v_cndmask_b32_e64 v23, v23, -v23, s[36:37]
	v_fmac_f32_e32 v23, v9, v47
	v_cndmask_b32_e64 v23, v23, v47, s[40:41]
	v_mul_f32_e32 v23, 0x3e38aa3b, v23
	v_cvt_pk_bf16_f32 v45, v45, v23
	v_lshl_add_u64 v[46:47], v[34:35], 0, v[16:17]
	global_store_dwordx2 v[46:47], v[44:45], off offset:512
	v_lshlrev_b32_e32 v45, 16, v39
	v_lshlrev_b32_e32 v44, 16, v38
	v_and_b32_e32 v39, 0xffff0000, v39
	v_and_b32_e32 v38, 0xffff0000, v38
	v_pk_mul_f32 v[46:47], v[38:39], v[38:39]
	s_nop 0
	v_pk_fma_f32 v[46:47], v[44:45], v[44:45], v[46:47]
	s_nop 0
	v_add_f32_e32 v17, v46, v47
	s_nop 1
	v_add_f32_dpp v17, v17, v17 quad_perm:[1,0,3,2] row_mask:0xf bank_mask:0xf bound_ctrl:1
	s_nop 1
	v_add_f32_dpp v17, v17, v17 quad_perm:[2,3,0,1] row_mask:0xf bank_mask:0xf bound_ctrl:1
	s_nop 1
	v_add_f32_dpp v17, v17, v17 row_ror:4 row_mask:0xf bank_mask:0xf bound_ctrl:1
	s_nop 1
	v_add_f32_dpp v17, v17, v17 row_ror:8 row_mask:0xf bank_mask:0xf bound_ctrl:1
	v_fmamk_f32 v17, v17, 0x3c800000, v237
	v_rsq_f32_e32 v46, v17
	s_nop 0
	v_mul_f32_e32 v17, v46, v44
	v_mul_f32_e32 v17, v4, v17
	s_nop 1
	v_mov_b32_dpp v23, v17 row_shr:4 row_mask:0xf bank_mask:0xa
	v_mov_b32_dpp v23, v17 row_shl:4 row_mask:0xf bank_mask:0x5
	v_mul_f32_e32 v23, v56, v23
	v_cndmask_b32_e64 v23, v23, -v23, s[36:37]
	v_fmac_f32_e32 v23, v51, v17
	v_cndmask_b32_e64 v17, v23, v17, s[40:41]
	v_mul_f32_e32 v23, v46, v38
	v_mul_f32_e32 v23, v5, v23
	s_nop 1
	v_mov_b32_dpp v38, v23 row_shr:4 row_mask:0xf bank_mask:0xa
	v_mov_b32_dpp v38, v23 row_shl:4 row_mask:0xf bank_mask:0x5
	v_mul_f32_e32 v38, v50, v38
	v_cndmask_b32_e64 v38, v38, -v38, s[36:37]
	v_fmac_f32_e32 v38, v49, v23
	v_cndmask_b32_e64 v23, v38, v23, s[40:41]
	v_mul_f32_e32 v38, v46, v45
	v_mul_f32_e32 v38, v6, v38
	s_nop 1
	v_mov_b32_dpp v44, v38 row_shr:4 row_mask:0xf bank_mask:0xa
	v_mov_b32_dpp v44, v38 row_shl:4 row_mask:0xf bank_mask:0x5
	v_mul_f32_e32 v44, v48, v44
	v_cndmask_b32_e64 v44, v44, -v44, s[36:37]
	v_fmac_f32_e32 v44, v25, v38
	v_cndmask_b32_e64 v25, v44, v38, s[40:41]
	v_mul_f32_e32 v38, v46, v39
	v_mul_f32_e32 v38, v7, v38
	s_nop 1
	v_mov_b32_dpp v39, v38 row_shr:4 row_mask:0xf bank_mask:0xa
	v_mov_b32_dpp v39, v38 row_shl:4 row_mask:0xf bank_mask:0x5
	v_mul_f32_e32 v21, v21, v39
	v_cndmask_b32_e64 v21, v21, -v21, s[36:37]
	v_fmac_f32_e32 v21, v9, v38
	v_cndmask_b32_e64 v9, v21, v38, s[40:41]
	s_and_saveexec_b64 s[0:1], vcc
	s_cbranch_execz .LBB0_477
	v_cvt_pk_bf16_f32 v39, v25, v9
	v_mov_b32_e32 v25, v161
	v_cvt_pk_bf16_f32 v38, v17, v23
	v_lshl_add_u64 v[34:35], v[34:35], 0, v[24:25]
	global_store_dwordx2 v[34:35], v[38:39], off offset:512
	s_branch .LBB0_477

.LBB0_528:
	s_or_b64 exec, exec, s[4:5]
	v_lshrrev_b32_e32 v9, 6, v9
	v_and_b32_e32 v19, 63, v160
	v_cndmask_b32_e64 v9, v19, v9, s[38:39]
	v_cvt_f32_ubyte0_e32 v9, v9
	v_mul_f32_e32 v19, v56, v9
	v_mul_f32_e32 v19, 0.15915494, v19
	v_cos_f32_e32 v48, v19
	v_sin_f32_e32 v49, v19
	v_mul_f32_e32 v19, v57, v9
	v_mul_f32_e32 v19, 0.15915494, v19
	v_lshlrev_b32_e32 v51, 16, v43
	v_lshlrev_b32_e32 v50, 16, v42
	v_and_b32_e32 v43, 0xffff0000, v43
	v_and_b32_e32 v42, 0xffff0000, v42
	v_cos_f32_e32 v46, v19
	v_sin_f32_e32 v47, v19
	v_mul_f32_e32 v19, v58, v9
	v_mul_f32_e32 v9, v59, v9
	v_pk_mul_f32 v[52:53], v[42:43], v[42:43]
	v_mul_f32_e32 v19, 0.15915494, v19
	v_mul_f32_e32 v9, 0.15915494, v9
	v_pk_fma_f32 v[52:53], v[50:51], v[50:51], v[52:53]
	v_cos_f32_e32 v44, v19
	v_sin_f32_e32 v45, v19
	v_cos_f32_e32 v19, v9
	v_sin_f32_e32 v23, v9
	v_add_f32_e32 v9, v52, v53
	v_mov_b32_e32 v53, v1
	s_nop 0
	v_add_f32_dpp v9, v9, v9 quad_perm:[1,0,3,2] row_mask:0xf bank_mask:0xf bound_ctrl:1
	s_nop 1
	v_add_f32_dpp v9, v9, v9 quad_perm:[2,3,0,1] row_mask:0xf bank_mask:0xf bound_ctrl:1
	s_nop 1
	v_add_f32_dpp v9, v9, v9 row_ror:4 row_mask:0xf bank_mask:0xf bound_ctrl:1
	s_nop 1
	v_add_f32_dpp v9, v9, v9 row_ror:8 row_mask:0xf bank_mask:0xf bound_ctrl:1
	v_fmamk_f32 v9, v9, 0x3c800000, v237
	v_rsq_f32_e32 v21, v9
	s_nop 0
	v_mul_f32_e32 v9, v21, v50
	v_mul_f32_e32 v9, v0, v9
	s_nop 1
	v_mov_b32_dpp v50, v9 row_shr:4 row_mask:0xf bank_mask:0xa
	v_mov_b32_dpp v50, v9 row_shl:4 row_mask:0xf bank_mask:0x5
	v_mul_f32_e32 v205, v21, v42
	s_waitcnt lgkmcnt(0)
	v_mul_f32_e32 v50, v49, v50
	v_cndmask_b32_e64 v50, v50, -v50, s[36:37]
	v_fmac_f32_e32 v50, v48, v9
	v_cndmask_b32_e64 v52, v50, v9, s[40:41]
	v_pk_mul_f32 v[52:53], v[52:53], v[204:205]
	s_nop 1
	v_mov_b32_dpp v9, v53 row_shr:4 row_mask:0xf bank_mask:0xa
	v_mov_b32_dpp v9, v53 row_shl:4 row_mask:0xf bank_mask:0x5
	v_mul_f32_e32 v205, v21, v51
	v_cndmask_b32_e64 v42, v52, v52, s[40:41]
	v_cndmask_b32_e64 v42, v42, v42, s[40:41]
	v_cndmask_b32_e64 v42, v42, v42, s[40:41]
	v_mul_f32_e32 v9, v47, v9
	v_cndmask_b32_e64 v9, v9, -v9, s[36:37]
	v_fmac_f32_e32 v9, v46, v53
	v_cndmask_b32_e64 v9, v9, v53, s[40:41]
	v_pk_mov_b32 v[50:51], v[8:9], v[2:3] op_sel:[1,0]
	s_nop 0
	v_pk_mul_f32 v[50:51], v[50:51], v[204:205]
	s_nop 1
	v_mov_b32_dpp v52, v51 row_shr:4 row_mask:0xf bank_mask:0xa
	v_mov_b32_dpp v52, v51 row_shl:4 row_mask:0xf bank_mask:0x5
	v_mov_b32_e32 v9, v50
	v_cndmask_b32_e64 v9, v9, v50, s[40:41]
	v_mul_f32_e32 v205, v21, v43
	v_mul_f32_e32 v52, v45, v52
	v_cndmask_b32_e64 v52, v52, -v52, s[36:37]
	v_fmac_f32_e32 v52, v44, v51
	v_cndmask_b32_e64 v50, v52, v51, s[40:41]
	v_mov_b32_e32 v51, v3
	v_pk_mul_f32 v[50:51], v[50:51], v[204:205]
	s_nop 1
	v_mov_b32_dpp v21, v51 row_shr:4 row_mask:0xf bank_mask:0xa
	v_mov_b32_dpp v21, v51 row_shl:4 row_mask:0xf bank_mask:0x5
	v_cndmask_b32_e64 v43, v50, v50, s[40:41]
	v_cndmask_b32_e64 v50, v9, v9, s[40:41]
	v_cvt_pk_bf16_f32 v42, v42, v50
	v_mul_f32_e32 v21, v23, v21
	v_cndmask_b32_e64 v21, v21, -v21, s[36:37]
	v_fmac_f32_e32 v21, v19, v51
	v_cndmask_b32_e64 v9, v21, v51, s[40:41]
	v_mul_f32_e32 v9, 0x3e38aa3b, v9
	v_mov_b32_e32 v21, v161
	v_cvt_pk_bf16_f32 v43, v43, v9
	v_lshl_add_u64 v[50:51], v[30:31], 0, v[20:21]
	global_store_dwordx2 v[50:51], v[42:43], off offset:512
	v_lshlrev_b32_e32 v43, 16, v41
	v_lshlrev_b32_e32 v42, 16, v40
	v_and_b32_e32 v41, 0xffff0000, v41
	v_and_b32_e32 v40, 0xffff0000, v40
	v_pk_mul_f32 v[50:51], v[40:41], v[40:41]
	s_nop 0
	v_pk_fma_f32 v[50:51], v[42:43], v[42:43], v[50:51]
	s_nop 0
	v_add_f32_e32 v9, v50, v51
	v_mov_b32_e32 v51, v1
	s_nop 0
	v_add_f32_dpp v9, v9, v9 quad_perm:[1,0,3,2] row_mask:0xf bank_mask:0xf bound_ctrl:1
	s_nop 1
	v_add_f32_dpp v9, v9, v9 quad_perm:[2,3,0,1] row_mask:0xf bank_mask:0xf bound_ctrl:1
	s_nop 1
	v_add_f32_dpp v9, v9, v9 row_ror:4 row_mask:0xf bank_mask:0xf bound_ctrl:1
	s_nop 1
	v_add_f32_dpp v9, v9, v9 row_ror:8 row_mask:0xf bank_mask:0xf bound_ctrl:1
	v_fmamk_f32 v9, v9, 0x3c800000, v237
	v_rsq_f32_e32 v21, v9
	s_nop 0
	v_mul_f32_e32 v9, v21, v42
	v_mul_f32_e32 v9, v0, v9
	s_nop 1
	v_mov_b32_dpp v42, v9 row_shr:4 row_mask:0xf bank_mask:0xa
	v_mov_b32_dpp v42, v9 row_shl:4 row_mask:0xf bank_mask:0x5
	v_mul_f32_e32 v205, v21, v40
	v_mul_f32_e32 v42, v49, v42
	v_cndmask_b32_e64 v42, v42, -v42, s[36:37]
	v_fmac_f32_e32 v42, v48, v9
	v_cndmask_b32_e64 v50, v42, v9, s[40:41]
	v_pk_mul_f32 v[50:51], v[50:51], v[204:205]
	s_nop 1
	v_mov_b32_dpp v9, v51 row_shr:4 row_mask:0xf bank_mask:0xa
	v_mov_b32_dpp v9, v51 row_shl:4 row_mask:0xf bank_mask:0x5
	v_mul_f32_e32 v205, v21, v43
	v_cndmask_b32_e64 v40, v50, v50, s[40:41]
	v_cndmask_b32_e64 v40, v40, v40, s[40:41]
	v_cndmask_b32_e64 v40, v40, v40, s[40:41]
	v_mul_f32_e32 v9, v47, v9
	v_cndmask_b32_e64 v9, v9, -v9, s[36:37]
	v_fmac_f32_e32 v9, v46, v51
	v_cndmask_b32_e64 v9, v9, v51, s[40:41]
	v_pk_mov_b32 v[42:43], v[8:9], v[2:3] op_sel:[1,0]
	s_nop 0
	v_pk_mul_f32 v[42:43], v[42:43], v[204:205]
	s_nop 1
	v_mov_b32_dpp v50, v43 row_shr:4 row_mask:0xf bank_mask:0xa
	v_mov_b32_dpp v50, v43 row_shl:4 row_mask:0xf bank_mask:0x5
	v_mov_b32_e32 v9, v42
	v_cndmask_b32_e64 v9, v9, v42, s[40:41]
	v_mul_f32_e32 v205, v21, v41
	v_cndmask_b32_e64 v9, v9, v9, s[40:41]
	v_mul_f32_e32 v50, v45, v50
	v_cndmask_b32_e64 v50, v50, -v50, s[36:37]
	v_fmac_f32_e32 v50, v44, v43
	v_cndmask_b32_e64 v42, v50, v43, s[40:41]
	v_mov_b32_e32 v43, v3
	v_pk_mul_f32 v[42:43], v[42:43], v[204:205]
	s_nop 1
	v_mov_b32_dpp v21, v43 row_shr:4 row_mask:0xf bank_mask:0xa
	v_mov_b32_dpp v21, v43 row_shl:4 row_mask:0xf bank_mask:0x5
	v_cndmask_b32_e64 v41, v42, v42, s[40:41]
	v_cvt_pk_bf16_f32 v40, v40, v9
	v_mov_b32_e32 v9, v161
	v_mul_f32_e32 v21, v23, v21
	v_cndmask_b32_e64 v21, v21, -v21, s[36:37]
	v_fmac_f32_e32 v21, v19, v43
	v_cndmask_b32_e64 v21, v21, v43, s[40:41]
	v_mul_f32_e32 v21, 0x3e38aa3b, v21
	v_cvt_pk_bf16_f32 v41, v41, v21
	v_lshl_add_u64 v[42:43], v[30:31], 0, v[8:9]
	global_store_dwordx2 v[42:43], v[40:41], off offset:512
	v_and_b32_e32 v43, 0xffff0000, v35
	v_and_b32_e32 v42, 0xffff0000, v34
	v_lshlrev_b32_e32 v41, 16, v35
	v_lshlrev_b32_e32 v40, 16, v34
	v_pk_mul_f32 v[34:35], v[42:43], v[42:43]
	s_nop 0
	v_pk_fma_f32 v[34:35], v[40:41], v[40:41], v[34:35]
	s_nop 0
	v_add_f32_e32 v9, v34, v35
	s_nop 1
	v_add_f32_dpp v9, v9, v9 quad_perm:[1,0,3,2] row_mask:0xf bank_mask:0xf bound_ctrl:1
	s_nop 1
	v_add_f32_dpp v9, v9, v9 quad_perm:[2,3,0,1] row_mask:0xf bank_mask:0xf bound_ctrl:1
	s_nop 1
	v_add_f32_dpp v9, v9, v9 row_ror:4 row_mask:0xf bank_mask:0xf bound_ctrl:1
	s_nop 1
	v_add_f32_dpp v9, v9, v9 row_ror:8 row_mask:0xf bank_mask:0xf bound_ctrl:1
	v_fmamk_f32 v9, v9, 0x3c800000, v237
	v_rsq_f32_e32 v9, v9
	s_nop 0
	v_mul_f32_e32 v21, v9, v40
	v_mul_f32_e32 v21, v4, v21
	s_nop 1
	v_mov_b32_dpp v34, v21 row_shr:4 row_mask:0xf bank_mask:0xa
	v_mov_b32_dpp v34, v21 row_shl:4 row_mask:0xf bank_mask:0x5
	v_mul_f32_e32 v34, v49, v34
	v_cndmask_b32_e64 v34, v34, -v34, s[36:37]
	v_fmac_f32_e32 v34, v48, v21
	v_cndmask_b32_e64 v21, v34, v21, s[40:41]
	v_mul_f32_e32 v34, v9, v42
	v_mul_f32_e32 v34, v5, v34
	s_nop 1
	v_mov_b32_dpp v35, v34 row_shr:4 row_mask:0xf bank_mask:0xa
	v_mov_b32_dpp v35, v34 row_shl:4 row_mask:0xf bank_mask:0x5
	v_mul_f32_e32 v35, v47, v35
	v_cndmask_b32_e64 v35, v35, -v35, s[36:37]
	v_fmac_f32_e32 v35, v46, v34
	v_cndmask_b32_e64 v34, v35, v34, s[40:41]
	v_mul_f32_e32 v35, v9, v41
	v_mul_f32_e32 v35, v6, v35
	s_nop 1
	v_mov_b32_dpp v40, v35 row_shr:4 row_mask:0xf bank_mask:0xa
	v_mov_b32_dpp v40, v35 row_shl:4 row_mask:0xf bank_mask:0x5
	v_mul_f32_e32 v9, v9, v43
	v_mul_f32_e32 v9, v7, v9
	v_mul_f32_e32 v40, v45, v40
	v_cndmask_b32_e64 v40, v40, -v40, s[36:37]
	v_fmac_f32_e32 v40, v44, v35
	v_cndmask_b32_e64 v35, v40, v35, s[40:41]
	s_nop 1
	v_mov_b32_dpp v40, v9 row_shr:4 row_mask:0xf bank_mask:0xa
	v_mov_b32_dpp v40, v9 row_shl:4 row_mask:0xf bank_mask:0x5
	v_mul_f32_e32 v23, v23, v40
	v_cndmask_b32_e64 v23, v23, -v23, s[36:37]
	v_fmac_f32_e32 v23, v19, v9
	v_cndmask_b32_e64 v9, v23, v9, s[40:41]
	s_and_saveexec_b64 s[0:1], vcc
	s_cbranch_execz .LBB0_507
	v_mov_b32_e32 v23, v161
	v_cvt_pk_bf16_f32 v34, v21, v34
	v_cvt_pk_bf16_f32 v35, v35, v9
	v_lshl_add_u64 v[30:31], v[30:31], 0, v[22:23]
	global_store_dwordx2 v[30:31], v[34:35], off offset:512
	s_branch .LBB0_507

.LBB0_554:
	s_or_b64 exec, exec, s[4:5]
	v_lshrrev_b32_e32 v9, 6, v9
	v_and_b32_e32 v19, 63, v24
	v_cndmask_b32_e64 v9, v19, v9, s[38:39]
	v_cvt_f32_ubyte0_e32 v9, v9
	v_mul_f32_e32 v19, v58, v9
	v_mul_f32_e32 v19, 0.15915494, v19
	v_cos_f32_e32 v50, v19
	v_sin_f32_e32 v51, v19
	v_mul_f32_e32 v19, v59, v9
	v_mul_f32_e32 v19, 0.15915494, v19
	v_lshlrev_b32_e32 v53, 16, v45
	v_lshlrev_b32_e32 v52, 16, v44
	v_and_b32_e32 v45, 0xffff0000, v45
	v_and_b32_e32 v44, 0xffff0000, v44
	v_cos_f32_e32 v48, v19
	v_sin_f32_e32 v49, v19
	v_mul_f32_e32 v19, v60, v9
	v_mul_f32_e32 v9, v61, v9
	v_pk_mul_f32 v[54:55], v[44:45], v[44:45]
	v_mul_f32_e32 v19, 0.15915494, v19
	v_mul_f32_e32 v9, 0.15915494, v9
	v_pk_fma_f32 v[54:55], v[52:53], v[52:53], v[54:55]
	v_cos_f32_e32 v46, v19
	v_sin_f32_e32 v47, v19
	v_cos_f32_e32 v19, v9
	v_sin_f32_e32 v23, v9
	v_add_f32_e32 v9, v54, v55
	v_mov_b32_e32 v55, v1
	s_nop 0
	v_add_f32_dpp v9, v9, v9 quad_perm:[1,0,3,2] row_mask:0xf bank_mask:0xf bound_ctrl:1
	s_nop 1
	v_add_f32_dpp v9, v9, v9 quad_perm:[2,3,0,1] row_mask:0xf bank_mask:0xf bound_ctrl:1
	s_nop 1
	v_add_f32_dpp v9, v9, v9 row_ror:4 row_mask:0xf bank_mask:0xf bound_ctrl:1
	s_nop 1
	v_add_f32_dpp v9, v9, v9 row_ror:8 row_mask:0xf bank_mask:0xf bound_ctrl:1
	v_fmamk_f32 v9, v9, 0x3c800000, v237
	v_rsq_f32_e32 v21, v9
	s_nop 0
	v_mul_f32_e32 v9, v21, v52
	v_mul_f32_e32 v9, v0, v9
	s_nop 1
	v_mov_b32_dpp v52, v9 row_shr:4 row_mask:0xf bank_mask:0xa
	v_mov_b32_dpp v52, v9 row_shl:4 row_mask:0xf bank_mask:0x5
	v_mul_f32_e32 v205, v21, v44
	s_waitcnt lgkmcnt(0)
	v_mul_f32_e32 v52, v51, v52
	v_cndmask_b32_e64 v52, v52, -v52, s[36:37]
	v_fmac_f32_e32 v52, v50, v9
	v_cndmask_b32_e64 v54, v52, v9, s[40:41]
	v_pk_mul_f32 v[54:55], v[54:55], v[204:205]
	s_nop 1
	v_mov_b32_dpp v9, v55 row_shr:4 row_mask:0xf bank_mask:0xa
	v_mov_b32_dpp v9, v55 row_shl:4 row_mask:0xf bank_mask:0x5
	v_mul_f32_e32 v205, v21, v53
	v_cndmask_b32_e64 v44, v54, v54, s[40:41]
	v_cndmask_b32_e64 v44, v44, v44, s[40:41]
	v_cndmask_b32_e64 v44, v44, v44, s[40:41]
	v_mul_f32_e32 v9, v49, v9
	v_cndmask_b32_e64 v9, v9, -v9, s[36:37]
	v_fmac_f32_e32 v9, v48, v55
	v_cndmask_b32_e64 v9, v9, v55, s[40:41]
	v_pk_mov_b32 v[52:53], v[8:9], v[2:3] op_sel:[1,0]
	s_nop 0
	v_pk_mul_f32 v[52:53], v[52:53], v[204:205]
	s_nop 1
	v_mov_b32_dpp v54, v53 row_shr:4 row_mask:0xf bank_mask:0xa
	v_mov_b32_dpp v54, v53 row_shl:4 row_mask:0xf bank_mask:0x5
	v_mov_b32_e32 v9, v52
	v_cndmask_b32_e64 v9, v9, v52, s[40:41]
	v_mul_f32_e32 v205, v21, v45
	v_mul_f32_e32 v54, v47, v54
	v_cndmask_b32_e64 v54, v54, -v54, s[36:37]
	v_fmac_f32_e32 v54, v46, v53
	v_cndmask_b32_e64 v52, v54, v53, s[40:41]
	v_mov_b32_e32 v53, v3
	v_pk_mul_f32 v[52:53], v[52:53], v[204:205]
	s_nop 1
	v_mov_b32_dpp v21, v53 row_shr:4 row_mask:0xf bank_mask:0xa
	v_mov_b32_dpp v21, v53 row_shl:4 row_mask:0xf bank_mask:0x5
	v_cndmask_b32_e64 v45, v52, v52, s[40:41]
	v_cndmask_b32_e64 v52, v9, v9, s[40:41]
	v_cvt_pk_bf16_f32 v44, v44, v52
	v_mul_f32_e32 v21, v23, v21
	v_cndmask_b32_e64 v21, v21, -v21, s[36:37]
	v_fmac_f32_e32 v21, v19, v53
	v_cndmask_b32_e64 v9, v21, v53, s[40:41]
	v_mul_f32_e32 v9, 0x3e38aa3b, v9
	v_mov_b32_e32 v21, v161
	v_cvt_pk_bf16_f32 v45, v45, v9
	v_lshl_add_u64 v[52:53], v[32:33], 0, v[20:21]
	global_store_dwordx2 v[52:53], v[44:45], off offset:512
	v_lshlrev_b32_e32 v45, 16, v43
	v_lshlrev_b32_e32 v44, 16, v42
	v_and_b32_e32 v43, 0xffff0000, v43
	v_and_b32_e32 v42, 0xffff0000, v42
	v_pk_mul_f32 v[52:53], v[42:43], v[42:43]
	s_nop 0
	v_pk_fma_f32 v[52:53], v[44:45], v[44:45], v[52:53]
	s_nop 0
	v_add_f32_e32 v9, v52, v53
	v_mov_b32_e32 v53, v1
	s_nop 0
	v_add_f32_dpp v9, v9, v9 quad_perm:[1,0,3,2] row_mask:0xf bank_mask:0xf bound_ctrl:1
	s_nop 1
	v_add_f32_dpp v9, v9, v9 quad_perm:[2,3,0,1] row_mask:0xf bank_mask:0xf bound_ctrl:1
	s_nop 1
	v_add_f32_dpp v9, v9, v9 row_ror:4 row_mask:0xf bank_mask:0xf bound_ctrl:1
	s_nop 1
	v_add_f32_dpp v9, v9, v9 row_ror:8 row_mask:0xf bank_mask:0xf bound_ctrl:1
	v_fmamk_f32 v9, v9, 0x3c800000, v237
	v_rsq_f32_e32 v21, v9
	s_nop 0
	v_mul_f32_e32 v9, v21, v44
	v_mul_f32_e32 v9, v0, v9
	s_nop 1
	v_mov_b32_dpp v44, v9 row_shr:4 row_mask:0xf bank_mask:0xa
	v_mov_b32_dpp v44, v9 row_shl:4 row_mask:0xf bank_mask:0x5
	v_mul_f32_e32 v205, v21, v42
	v_mul_f32_e32 v44, v51, v44
	v_cndmask_b32_e64 v44, v44, -v44, s[36:37]
	v_fmac_f32_e32 v44, v50, v9
	v_cndmask_b32_e64 v52, v44, v9, s[40:41]
	v_pk_mul_f32 v[52:53], v[52:53], v[204:205]
	s_nop 1
	v_mov_b32_dpp v9, v53 row_shr:4 row_mask:0xf bank_mask:0xa
	v_mov_b32_dpp v9, v53 row_shl:4 row_mask:0xf bank_mask:0x5
	v_mul_f32_e32 v205, v21, v45
	v_cndmask_b32_e64 v42, v52, v52, s[40:41]
	v_cndmask_b32_e64 v42, v42, v42, s[40:41]
	v_cndmask_b32_e64 v42, v42, v42, s[40:41]
	v_mul_f32_e32 v9, v49, v9
	v_cndmask_b32_e64 v9, v9, -v9, s[36:37]
	v_fmac_f32_e32 v9, v48, v53
	v_cndmask_b32_e64 v9, v9, v53, s[40:41]
	v_pk_mov_b32 v[44:45], v[8:9], v[2:3] op_sel:[1,0]
	s_nop 0
	v_pk_mul_f32 v[44:45], v[44:45], v[204:205]
	s_nop 1
	v_mov_b32_dpp v52, v45 row_shr:4 row_mask:0xf bank_mask:0xa
	v_mov_b32_dpp v52, v45 row_shl:4 row_mask:0xf bank_mask:0x5
	v_mov_b32_e32 v9, v44
	v_cndmask_b32_e64 v9, v9, v44, s[40:41]
	v_mul_f32_e32 v205, v21, v43
	v_cndmask_b32_e64 v9, v9, v9, s[40:41]
	v_mul_f32_e32 v52, v47, v52
	v_cndmask_b32_e64 v52, v52, -v52, s[36:37]
	v_fmac_f32_e32 v52, v46, v45
	v_cndmask_b32_e64 v44, v52, v45, s[40:41]
	v_mov_b32_e32 v45, v3
	v_pk_mul_f32 v[44:45], v[44:45], v[204:205]
	s_nop 1
	v_mov_b32_dpp v21, v45 row_shr:4 row_mask:0xf bank_mask:0xa
	v_mov_b32_dpp v21, v45 row_shl:4 row_mask:0xf bank_mask:0x5
	v_cndmask_b32_e64 v43, v44, v44, s[40:41]
	v_cvt_pk_bf16_f32 v42, v42, v9
	v_mov_b32_e32 v9, v161
	v_mul_f32_e32 v21, v23, v21
	v_cndmask_b32_e64 v21, v21, -v21, s[36:37]
	v_fmac_f32_e32 v21, v19, v45
	v_cndmask_b32_e64 v21, v21, v45, s[40:41]
	v_mul_f32_e32 v21, 0x3e38aa3b, v21
	v_cvt_pk_bf16_f32 v43, v43, v21
	v_lshl_add_u64 v[44:45], v[32:33], 0, v[8:9]
	global_store_dwordx2 v[44:45], v[42:43], off offset:512
	v_and_b32_e32 v45, 0xffff0000, v37
	v_and_b32_e32 v44, 0xffff0000, v36
	v_lshlrev_b32_e32 v43, 16, v37
	v_lshlrev_b32_e32 v42, 16, v36
	v_pk_mul_f32 v[36:37], v[44:45], v[44:45]
	s_nop 0
	v_pk_fma_f32 v[36:37], v[42:43], v[42:43], v[36:37]
	s_nop 0
	v_add_f32_e32 v9, v36, v37
	s_nop 1
	v_add_f32_dpp v9, v9, v9 quad_perm:[1,0,3,2] row_mask:0xf bank_mask:0xf bound_ctrl:1
	s_nop 1
	v_add_f32_dpp v9, v9, v9 quad_perm:[2,3,0,1] row_mask:0xf bank_mask:0xf bound_ctrl:1
	s_nop 1
	v_add_f32_dpp v9, v9, v9 row_ror:4 row_mask:0xf bank_mask:0xf bound_ctrl:1
	s_nop 1
	v_add_f32_dpp v9, v9, v9 row_ror:8 row_mask:0xf bank_mask:0xf bound_ctrl:1
	v_fmamk_f32 v9, v9, 0x3c800000, v237
	v_rsq_f32_e32 v9, v9
	s_nop 0
	v_mul_f32_e32 v21, v9, v42
	v_mul_f32_e32 v21, v4, v21
	s_nop 1
	v_mov_b32_dpp v36, v21 row_shr:4 row_mask:0xf bank_mask:0xa
	v_mov_b32_dpp v36, v21 row_shl:4 row_mask:0xf bank_mask:0x5
	v_mul_f32_e32 v36, v51, v36
	v_cndmask_b32_e64 v36, v36, -v36, s[36:37]
	v_fmac_f32_e32 v36, v50, v21
	v_cndmask_b32_e64 v21, v36, v21, s[40:41]
	v_mul_f32_e32 v36, v9, v44
	v_mul_f32_e32 v36, v5, v36
	s_nop 1
	v_mov_b32_dpp v37, v36 row_shr:4 row_mask:0xf bank_mask:0xa
	v_mov_b32_dpp v37, v36 row_shl:4 row_mask:0xf bank_mask:0x5
	v_mul_f32_e32 v37, v49, v37
	v_cndmask_b32_e64 v37, v37, -v37, s[36:37]
	v_fmac_f32_e32 v37, v48, v36
	v_cndmask_b32_e64 v36, v37, v36, s[40:41]
	v_mul_f32_e32 v37, v9, v43
	v_mul_f32_e32 v37, v6, v37
	s_nop 1
	v_mov_b32_dpp v42, v37 row_shr:4 row_mask:0xf bank_mask:0xa
	v_mov_b32_dpp v42, v37 row_shl:4 row_mask:0xf bank_mask:0x5
	v_mul_f32_e32 v9, v9, v45
	v_mul_f32_e32 v9, v7, v9
	v_mul_f32_e32 v42, v47, v42
	v_cndmask_b32_e64 v42, v42, -v42, s[36:37]
	v_fmac_f32_e32 v42, v46, v37
	v_cndmask_b32_e64 v37, v42, v37, s[40:41]
	s_nop 1
	v_mov_b32_dpp v42, v9 row_shr:4 row_mask:0xf bank_mask:0xa
	v_mov_b32_dpp v42, v9 row_shl:4 row_mask:0xf bank_mask:0x5
	v_mul_f32_e32 v23, v23, v42
	v_cndmask_b32_e64 v23, v23, -v23, s[36:37]
	v_fmac_f32_e32 v23, v19, v9
	v_cndmask_b32_e64 v9, v23, v9, s[40:41]
	s_and_saveexec_b64 s[0:1], vcc
	s_cbranch_execz .LBB0_533
	v_mov_b32_e32 v23, v161
	v_cvt_pk_bf16_f32 v36, v21, v36
	v_cvt_pk_bf16_f32 v37, v37, v9
	v_lshl_add_u64 v[32:33], v[32:33], 0, v[22:23]
	global_store_dwordx2 v[32:33], v[36:37], off offset:512
	s_branch .LBB0_533
